# speedup vs baseline: 1.0228x; 1.0085x over previous
; __device__ __forceinline__ void attn_exp(f32x16& sa, float mx, float& m_run, float& lsum, f32x16 (&o)[4], bf16x8& pb0, bf16x8& pb1) {
;     ...
;     float pv[16];
; #pragma unroll
;     for (int r = 0; r < 16; ++r) { pv[r] = __builtin_amdgcn_exp2f(sa[r] - m_run); lsum += pv[r]; }
;     u32x4 t0 = {pack2(pv[0], pv[1]), pack2(pv[2], pv[3]), pack2(pv[4], pv[5]), pack2(pv[6], pv[7])};
;     u32x4 t1 = {pack2(pv[8], pv[9]), pack2(pv[10], pv[11]), pack2(pv[12], pv[13]), pack2(pv[14], pv[15])};
;     pb0 = __builtin_bit_cast(bf16x8, t0);
;     pb1 = __builtin_bit_cast(bf16x8, t1);
; template <bool MLA>
; __device__ __forceinline__ void attn_meta_item(unsigned char* smem, const Params& p, int b, int hh, int quarter, int aslot) {
;     ...
;     for (int ib = 0; ib < nblk; ++ib) {
;         const int kb = ib < 4 ? quarter * 32 + w * 4 + ib : 128;
;         const int k0 = kb * 32;
;         f32x16 sa;
; #pragma unroll
;         for (int r = 0; r < 16; ++r) sa[r] = 0.f;
; #pragma unroll
;         for (int s = 0; s < NS; ++s) {
;             const bf16_t* src;
;             if constexpr (MLA) src = s < 8 ? k1 + (size_t)(k0 + l31) * 2048 + s * 16 + h5 * 8 : k2 + (size_t)(k0 + l31) * 64 + (s - 8) * 16 + h5 * 8;
;             else src = k1 + (size_t)(k0 + l31) * 2048 + s * 16 + h5 * 8;
;             bf16x8 kf = *(const bf16x8*)src;
;             sa = __builtin_amdgcn_mfma_f32_32x32x16_bf16(kf, qf[s], sa, 0, 0, 0);
;         }
;         bf16x8 pb0, pb1;
;         attn_softmax<MLA>(sa, c1, slope2, qpos, 0, k0, h5, kb == 128, m_run, lsum, o, pb0, pb1);
; #pragma unroll
;         for (int d = 0; d < 4; ++d) {
;             bf16x8 vf0 = *(const bf16x8*)(vt + (size_t)(d * 32 + l31) * LP + k0 + h5 * 8);
;             bf16x8 vf1 = *(const bf16x8*)(vt + (size_t)(d * 32 + l31) * LP + k0 + 16 + h5 * 8);
;             o[d] = __builtin_amdgcn_mfma_f32_32x32x16_bf16(vf0, pb0, o[d], 0, 0, 0);
;             o[d] = __builtin_amdgcn_mfma_f32_32x32x16_bf16(vf1, pb1, o[d], 0, 0, 0);
;         }
.LBB0_836:
	v_ashrrev_i32_e32 v137, 31, v136
	v_lshl_add_u64 v[230:231], v[136:137], 1, v[132:133]
	v_lshl_add_u64 v[136:137], v[230:231], 0, v[0:1]
	s_mov_b32 s0, 0x41000
	v_add_co_u32_e32 v230, vcc, s0, v136
	s_mov_b32 s0, 0x82000
	s_nop 0
	v_addc_co_u32_e32 v231, vcc, 0, v137, vcc
	v_add_co_u32_e32 v232, vcc, s0, v136
	s_mov_b32 s0, 0xc3000
	s_nop 0
	v_addc_co_u32_e32 v233, vcc, 0, v137, vcc
	v_add_co_u32_e32 v234, vcc, s0, v136
	s_nop 1
	v_addc_co_u32_e32 v235, vcc, 0, v137, vcc
	global_load_dwordx4 v[192:195], v[136:137], off
	global_load_dwordx4 v[196:199], v[136:137], off offset:32
	global_load_dwordx4 v[200:203], v[230:231], off
	global_load_dwordx4 v[204:207], v[230:231], off offset:32
	global_load_dwordx4 v[208:211], v[232:233], off
	global_load_dwordx4 v[212:215], v[232:233], off offset:32
	global_load_dwordx4 v[222:225], v[234:235], off
	global_load_dwordx4 v[226:229], v[234:235], off offset:32
	v_sub_f32_e32 v66, v66, v147
	v_exp_f32_e32 v149, v66
	v_sub_f32_e32 v66, v67, v147
	v_exp_f32_e32 v150, v66
	v_sub_f32_e32 v66, v68, v147
	v_exp_f32_e32 v151, v66
	v_sub_f32_e32 v66, v69, v147
	v_exp_f32_e32 v152, v66
	v_sub_f32_e32 v66, v70, v147
	v_exp_f32_e32 v153, v66
	v_sub_f32_e32 v66, v71, v147
	v_exp_f32_e32 v154, v66
	v_sub_f32_e32 v66, v72, v147
	v_exp_f32_e32 v155, v66
	v_sub_f32_e32 v66, v73, v147
	v_exp_f32_e32 v156, v66
	v_sub_f32_e32 v66, v74, v147
	v_exp_f32_e32 v157, v66
	v_sub_f32_e32 v66, v75, v147
	v_exp_f32_e32 v158, v66
	v_sub_f32_e32 v66, v76, v147
	v_exp_f32_e32 v159, v66
	v_sub_f32_e32 v66, v77, v147
	v_exp_f32_e32 v160, v66
	v_sub_f32_e32 v66, v78, v147
	v_exp_f32_e32 v161, v66
	v_sub_f32_e32 v66, v79, v147
	v_exp_f32_e32 v162, v66
	v_sub_f32_e32 v66, v80, v147
	v_exp_f32_e32 v163, v66
	v_sub_f32_e32 v66, v81, v147
	v_exp_f32_e32 v164, v66
	v_cvt_pk_bf16_f32 v66, v149, v150
	v_cvt_pk_bf16_f32 v67, v151, v152
	v_cvt_pk_bf16_f32 v68, v153, v154
	v_cvt_pk_bf16_f32 v69, v155, v156
	v_cvt_pk_bf16_f32 v70, v157, v158
	v_cvt_pk_bf16_f32 v71, v159, v160
	v_cvt_pk_bf16_f32 v72, v161, v162
	v_cvt_pk_bf16_f32 v73, v163, v164
	s_add_i32 s8, s8, 1
	v_cmp_eq_u32_e32 vcc, s8, v142
	s_or_b64 s[6:7], vcc, s[6:7]
	v_add_f32_e32 v230, v141, v149
	v_add_f32_e32 v230, v150, v230
	v_add_f32_e32 v230, v151, v230
	v_add_f32_e32 v230, v152, v230
	v_add_f32_e32 v230, v153, v230
	v_add_f32_e32 v230, v154, v230
	v_add_f32_e32 v230, v155, v230
	v_add_f32_e32 v230, v156, v230
	v_add_f32_e32 v230, v157, v230
	v_add_f32_e32 v230, v158, v230
	v_add_f32_e32 v230, v159, v230
	v_add_f32_e32 v230, v160, v230
	v_add_f32_e32 v230, v161, v230
	v_add_f32_e32 v230, v162, v230
	v_add_f32_e32 v230, v163, v230
	v_add_f32_e32 v141, v164, v230
	s_waitcnt vmcnt(7)
	v_mfma_f32_32x32x16_bf16 v[50:65], v[192:195], v[66:69], v[50:65]
	s_waitcnt vmcnt(6)
	v_mfma_f32_32x32x16_bf16 v[50:65], v[196:199], v[70:73], v[50:65]
	s_waitcnt vmcnt(5)
	v_mfma_f32_32x32x16_bf16 v[34:49], v[200:203], v[66:69], v[34:49]
	s_waitcnt vmcnt(4)
	v_mfma_f32_32x32x16_bf16 v[34:49], v[204:207], v[70:73], v[34:49]
	s_waitcnt vmcnt(3)
	v_mfma_f32_32x32x16_bf16 v[18:33], v[208:211], v[66:69], v[18:33]
	s_waitcnt vmcnt(2)
	v_mfma_f32_32x32x16_bf16 v[18:33], v[212:215], v[70:73], v[18:33]
	s_waitcnt vmcnt(1)
	v_mfma_f32_32x32x16_bf16 v[2:17], v[222:225], v[66:69], v[2:17]
	s_waitcnt vmcnt(0)
	v_mfma_f32_32x32x16_bf16 v[2:17], v[226:229], v[70:73], v[2:17]
	s_andn2_b64 exec, exec, s[6:7]
	s_cbranch_execz .LBB0_839
.LBB0_837:
	s_cmp_lt_u32 s8, 4
	s_cselect_b64 vcc, -1, 0
	v_add_u32_e32 v66, s8, v145
	v_cndmask_b32_e32 v137, v184, v66, vcc
	v_lshlrev_b32_e32 v136, 5, v137
	v_or_b32_e32 v66, v136, v140
	v_ashrrev_i32_e32 v67, 31, v66
	v_lshlrev_b64 v[68:69], 7, v[66:67]
	v_lshlrev_b64 v[66:67], 12, v[66:67]
	v_lshl_add_u64 v[156:157], v[134:135], 0, v[66:67]
	v_lshl_add_u64 v[154:155], s[2:3], 0, v[68:69]
	s_mov_b32 s0, 0x5580000
	s_movk_i32 s9, 0x100f
	v_lshl_add_u64 v[150:151], v[154:155], 0, v[0:1]
	v_add_co_u32_e32 v154, vcc, s0, v150
	s_movk_i32 s0, 0x80
	s_nop 0
	v_addc_co_u32_e32 v155, vcc, 0, v151, vcc
	global_load_dwordx4 v[66:69], v[156:157], off
	global_load_dwordx4 v[192:195], v[156:157], off offset:32
	global_load_dwordx4 v[196:199], v[156:157], off offset:64
	global_load_dwordx4 v[200:203], v[156:157], off offset:96
	global_load_dwordx4 v[204:207], v[156:157], off offset:128
	global_load_dwordx4 v[208:211], v[156:157], off offset:160
	global_load_dwordx4 v[212:215], v[156:157], off offset:192
	global_load_dwordx4 v[222:225], v[156:157], off offset:224
	global_load_dwordx4 v[226:229], v[154:155], off
	global_load_dwordx4 v[230:233], v[154:155], off offset:32
	global_load_dwordx4 v[234:237], v[154:155], off offset:64
	global_load_dwordx4 v[150:153], v[154:155], off offset:96
	v_cmp_eq_u32_e32 vcc, s0, v137
	v_or_b32_e32 v137, v136, v143
	v_cmp_lt_i32_e64 s[0:1], s9, v137
	s_and_b64 s[0:1], vcc, s[0:1]
	v_or_b32_e32 v149, 2, v137
	s_waitcnt vmcnt(11)
	v_mfma_f32_32x32x16_bf16 v[66:81], v[66:69], v[82:85], 0
	s_waitcnt vmcnt(10)
	v_mfma_f32_32x32x16_bf16 v[66:81], v[192:195], v[86:89], v[66:81]
	s_waitcnt vmcnt(9)
	v_mfma_f32_32x32x16_bf16 v[66:81], v[196:199], v[90:93], v[66:81]
	s_waitcnt vmcnt(8)
	v_mfma_f32_32x32x16_bf16 v[66:81], v[200:203], v[94:97], v[66:81]
	s_waitcnt vmcnt(7)
	v_mfma_f32_32x32x16_bf16 v[66:81], v[204:207], v[98:101], v[66:81]
	s_waitcnt vmcnt(6)
	v_mfma_f32_32x32x16_bf16 v[66:81], v[208:211], v[102:105], v[66:81]
	s_waitcnt vmcnt(5)
	v_mfma_f32_32x32x16_bf16 v[66:81], v[212:215], v[106:109], v[66:81]
	s_waitcnt vmcnt(4)
	v_mfma_f32_32x32x16_bf16 v[66:81], v[222:225], v[110:113], v[66:81]
	s_waitcnt vmcnt(3)
; template <bool MLA>
; __device__ __forceinline__ float attn_scores(f32x16& sa, float c1, float slope2, int qpos, int q0w, int kpos0, int h5, bool maskit) {
;     float mx = -INFINITY;
;     if constexpr (MLA) {
; #pragma unroll
;         for (int r = 0; r < 16; ++r) {
;             float v = sa[r] * c1;
;             if (maskit && (kpos0 + 8 * (r >> 2) + (r & 3) + 4 * h5 >= L)) v = -INFINITY;
;             sa[r] = v;
;             mx = fmaxf(mx, v);
;         }
;     } else {
;         const float dq = (float)(qpos - kpos0 - 4 * h5);
;         const int rel = q0w - kpos0;
;         if (rel > 31 || rel < -31) {
;             const float sgn = rel > 0 ? 1.0f : -1.0f;
;             const float A = -sgn * slope2 * dq;
;             const float ss = sgn * slope2;
; #pragma unroll
;             for (int r = 0; r < 16; ++r) {
;                 const float ko = (float)(8 * (r >> 2) + (r & 3));
;                 float v = fmaf(sa[r], c1, fmaf(ss, ko, A));
;                 if (maskit && (kpos0 + 8 * (r >> 2) + (r & 3) + 4 * h5 >= L)) v = -INFINITY;
;                 sa[r] = v;
;                 mx = fmaxf(mx, v);
;             }
;         } else {
; #pragma unroll
;             for (int r = 0; r < 16; ++r) {
;                 const int ko = 8 * (r >> 2) + (r & 3);
;                 float v = sa[r] * c1 - slope2 * fabsf(dq - (float)ko);
;                 if (maskit && (kpos0 + ko + 4 * h5 >= L)) v = -INFINITY;
;                 sa[r] = v;
;                 mx = fmaxf(mx, v);
;             }
;         }
;     }
;     mx = fmaxf(mx, __shfl_xor(mx, 32));
;     return mx;
; }
; __device__ __forceinline__ void attn_exp(f32x16& sa, float mx, float& m_run, float& lsum, f32x16 (&o)[4], bf16x8& pb0, bf16x8& pb1) {
;     if (!__all(mx <= m_run + ATT_THR)) {
; template <bool MLA>
; __device__ __forceinline__ void attn_meta_item(unsigned char* smem, const Params& p, int b, int hh, int quarter, int aslot) {
;     ...
;         for (int s = 0; s < NS; ++s) {
;             const bf16_t* src;
;             if constexpr (MLA) src = s < 8 ? k1 + (size_t)(k0 + l31) * 2048 + s * 16 + h5 * 8 : k2 + (size_t)(k0 + l31) * 64 + (s - 8) * 16 + h5 * 8;
;             else src = k1 + (size_t)(k0 + l31) * 2048 + s * 16 + h5 * 8;
;             bf16x8 kf = *(const bf16x8*)src;
;             sa = __builtin_amdgcn_mfma_f32_32x32x16_bf16(kf, qf[s], sa, 0, 0, 0);
;         }
	v_mfma_f32_32x32x16_bf16 v[66:81], v[226:229], v[118:121], v[66:81]
	s_waitcnt vmcnt(2)
	v_mfma_f32_32x32x16_bf16 v[66:81], v[230:233], v[126:129], v[66:81]
	s_waitcnt vmcnt(1)
	v_mfma_f32_32x32x16_bf16 v[66:81], v[234:237], v[114:117], v[66:81]
	s_waitcnt vmcnt(0)
	v_mfma_f32_32x32x16_bf16 v[66:81], v[150:153], v[122:125], v[66:81]
	s_nop 11
	v_mul_f32_e32 v66, 0x3dd53b94, v66
	v_cndmask_b32_e64 v66, v66, v177, s[0:1]
	s_movk_i32 s0, 0x100e
	v_cmp_lt_i32_e64 s[0:1], s0, v137
	v_mul_f32_e32 v67, 0x3dd53b94, v67
	s_and_b64 s[0:1], vcc, s[0:1]
	v_cndmask_b32_e64 v67, v67, v177, s[0:1]
	v_cmp_lt_i32_e64 s[0:1], s9, v149
	v_mul_f32_e32 v68, 0x3dd53b94, v68
	s_and_b64 s[0:1], vcc, s[0:1]
	v_or_b32_e32 v149, 3, v137
	v_cndmask_b32_e64 v68, v68, v177, s[0:1]
	v_cmp_lt_i32_e64 s[0:1], s9, v149
	v_mul_f32_e32 v69, 0x3dd53b94, v69
	s_and_b64 s[0:1], vcc, s[0:1]
	v_or_b32_e32 v149, 8, v137
	v_cndmask_b32_e64 v69, v69, v177, s[0:1]
	v_cmp_lt_i32_e64 s[0:1], s9, v149
	v_mul_f32_e32 v70, 0x3dd53b94, v70
	s_and_b64 s[0:1], vcc, s[0:1]
	v_or_b32_e32 v149, 9, v137
	v_cndmask_b32_e64 v70, v70, v177, s[0:1]
	v_cmp_lt_i32_e64 s[0:1], s9, v149
	v_mul_f32_e32 v71, 0x3dd53b94, v71
	s_and_b64 s[0:1], vcc, s[0:1]
	v_or_b32_e32 v149, 10, v137
	v_cndmask_b32_e64 v71, v71, v177, s[0:1]
	v_cmp_lt_i32_e64 s[0:1], s9, v149
	v_mul_f32_e32 v72, 0x3dd53b94, v72
	s_and_b64 s[0:1], vcc, s[0:1]
	v_or_b32_e32 v149, 11, v137
	v_cndmask_b32_e64 v72, v72, v177, s[0:1]
	v_cmp_lt_i32_e64 s[0:1], s9, v149
	v_mul_f32_e32 v73, 0x3dd53b94, v73
	s_and_b64 s[0:1], vcc, s[0:1]
	v_or_b32_e32 v149, 16, v137
	v_cndmask_b32_e64 v73, v73, v177, s[0:1]
	v_cmp_lt_i32_e64 s[0:1], s9, v149
	v_mul_f32_e32 v74, 0x3dd53b94, v74
	s_and_b64 s[0:1], vcc, s[0:1]
	v_or_b32_e32 v149, 17, v137
	v_cndmask_b32_e64 v74, v74, v177, s[0:1]
	v_cmp_lt_i32_e64 s[0:1], s9, v149
	v_mul_f32_e32 v75, 0x3dd53b94, v75
	s_and_b64 s[0:1], vcc, s[0:1]
	v_or_b32_e32 v149, 18, v137
	v_cndmask_b32_e64 v75, v75, v177, s[0:1]
	v_cmp_lt_i32_e64 s[0:1], s9, v149
	v_mul_f32_e32 v76, 0x3dd53b94, v76
	s_and_b64 s[0:1], vcc, s[0:1]
	v_or_b32_e32 v149, 19, v137
	v_cndmask_b32_e64 v76, v76, v177, s[0:1]
	v_cmp_lt_i32_e64 s[0:1], s9, v149
	v_mul_f32_e32 v77, 0x3dd53b94, v77
	s_and_b64 s[0:1], vcc, s[0:1]
	v_or_b32_e32 v149, 24, v137
	v_cndmask_b32_e64 v77, v77, v177, s[0:1]
	v_cmp_lt_i32_e64 s[0:1], s9, v149
	v_mul_f32_e32 v78, 0x3dd53b94, v78
	s_and_b64 s[0:1], vcc, s[0:1]
	v_or_b32_e32 v149, 25, v137
	v_cndmask_b32_e64 v78, v78, v177, s[0:1]
	v_cmp_lt_i32_e64 s[0:1], s9, v149
	v_mul_f32_e32 v79, 0x3dd53b94, v79
	s_and_b64 s[0:1], vcc, s[0:1]
	v_or_b32_e32 v149, 26, v137
	v_cndmask_b32_e64 v79, v79, v177, s[0:1]
	v_cmp_lt_i32_e64 s[0:1], s9, v149
	v_mul_f32_e32 v80, 0x3dd53b94, v80
	s_and_b64 s[0:1], vcc, s[0:1]
	v_or_b32_e32 v137, 27, v137
	v_cndmask_b32_e64 v80, v80, v177, s[0:1]
	v_cmp_lt_i32_e64 s[0:1], s9, v137
	s_and_b64 vcc, vcc, s[0:1]
	s_mov_b32 s0, 0xff800000
	v_max3_f32 v137, v66, s0, v67
	v_max3_f32 v137, v137, v68, v69
	v_max3_f32 v137, v137, v70, v71
	v_max3_f32 v137, v137, v72, v73
	v_max3_f32 v137, v137, v74, v75
	v_mul_f32_e32 v81, 0x3dd53b94, v81
	v_max3_f32 v137, v137, v76, v77
	v_cndmask_b32_e32 v81, v81, v177, vcc
	v_max3_f32 v137, v137, v78, v79
	v_max3_f32 v137, v137, v80, v81
	ds_bpermute_b32 v149, v144, v137
	s_waitcnt lgkmcnt(0)
	v_max_f32_e32 v149, v149, v149
	v_max_f32_e32 v137, v137, v149
	v_add_f32_e32 v149, 0x41000000, v147
	v_cmp_le_f32_e32 vcc, v137, v149
	s_cmp_eq_u64 vcc, exec
	s_cbranch_scc1 .LBB0_836
	v_max_f32_e32 v137, v137, v137
	v_max_f32_e32 v149, v147, v147
	v_max_f32_e32 v137, v149, v137
	v_sub_f32_e32 v147, v147, v137
	v_exp_f32_e32 v150, v147
	v_mov_b32_e32 v147, v137
	v_mul_f32_e32 v141, v141, v150
	v_pk_mul_f32 v[64:65], v[64:65], v[150:151] op_sel_hi:[1,0]
	v_pk_mul_f32 v[62:63], v[62:63], v[150:151] op_sel_hi:[1,0]
	v_pk_mul_f32 v[60:61], v[60:61], v[150:151] op_sel_hi:[1,0]
	v_pk_mul_f32 v[58:59], v[58:59], v[150:151] op_sel_hi:[1,0]
	v_pk_mul_f32 v[56:57], v[56:57], v[150:151] op_sel_hi:[1,0]
	v_pk_mul_f32 v[54:55], v[54:55], v[150:151] op_sel_hi:[1,0]
	v_pk_mul_f32 v[52:53], v[52:53], v[150:151] op_sel_hi:[1,0]
	v_pk_mul_f32 v[50:51], v[50:51], v[150:151] op_sel_hi:[1,0]
	v_pk_mul_f32 v[48:49], v[48:49], v[150:151] op_sel_hi:[1,0]
	v_pk_mul_f32 v[46:47], v[46:47], v[150:151] op_sel_hi:[1,0]
	v_pk_mul_f32 v[44:45], v[44:45], v[150:151] op_sel_hi:[1,0]
	v_pk_mul_f32 v[42:43], v[42:43], v[150:151] op_sel_hi:[1,0]
	v_pk_mul_f32 v[40:41], v[40:41], v[150:151] op_sel_hi:[1,0]
	v_pk_mul_f32 v[38:39], v[38:39], v[150:151] op_sel_hi:[1,0]
	v_pk_mul_f32 v[36:37], v[36:37], v[150:151] op_sel_hi:[1,0]
	v_pk_mul_f32 v[34:35], v[34:35], v[150:151] op_sel_hi:[1,0]
	v_pk_mul_f32 v[32:33], v[32:33], v[150:151] op_sel_hi:[1,0]
	v_pk_mul_f32 v[30:31], v[30:31], v[150:151] op_sel_hi:[1,0]
	v_pk_mul_f32 v[28:29], v[28:29], v[150:151] op_sel_hi:[1,0]
	v_pk_mul_f32 v[26:27], v[26:27], v[150:151] op_sel_hi:[1,0]
	v_pk_mul_f32 v[24:25], v[24:25], v[150:151] op_sel_hi:[1,0]
	v_pk_mul_f32 v[22:23], v[22:23], v[150:151] op_sel_hi:[1,0]
	v_pk_mul_f32 v[20:21], v[20:21], v[150:151] op_sel_hi:[1,0]
	v_pk_mul_f32 v[18:19], v[18:19], v[150:151] op_sel_hi:[1,0]
	v_pk_mul_f32 v[16:17], v[16:17], v[150:151] op_sel_hi:[1,0]
	v_pk_mul_f32 v[14:15], v[14:15], v[150:151] op_sel_hi:[1,0]
	v_pk_mul_f32 v[12:13], v[12:13], v[150:151] op_sel_hi:[1,0]
	v_pk_mul_f32 v[10:11], v[10:11], v[150:151] op_sel_hi:[1,0]
	v_pk_mul_f32 v[8:9], v[8:9], v[150:151] op_sel_hi:[1,0]
	v_pk_mul_f32 v[6:7], v[6:7], v[150:151] op_sel_hi:[1,0]
	v_pk_mul_f32 v[4:5], v[4:5], v[150:151] op_sel_hi:[1,0]
	v_pk_mul_f32 v[2:3], v[2:3], v[150:151] op_sel_hi:[1,0]
	s_branch .LBB0_836
